# bg conversion start delayed by 2x s_sleep 75 (about 3us) after barrier entry
# baseline (speedup 1.0000x reference)
.LBB0_434:
	v_lshl_add_u32 v192, s13, 8, v220
	v_ashrrev_i32_e32 v193, 31, v192
	v_lshlrev_b64 v[200:201], 6, v[192:193]
	v_lshl_add_u64 v[132:133], v[170:171], 0, v[200:201]
	global_load_dwordx4 v[132:135], v[132:133], off
	v_or_b32_e32 v190, 16, v192
	v_ashrrev_i32_e32 v191, 31, v190
	v_lshlrev_b64 v[202:203], 6, v[190:191]
	v_lshl_add_u64 v[136:137], v[170:171], 0, v[202:203]
	global_load_dwordx4 v[136:139], v[136:137], off
	v_or_b32_e32 v188, 32, v192
	v_ashrrev_i32_e32 v189, 31, v188
	v_lshlrev_b64 v[204:205], 6, v[188:189]
	v_lshl_add_u64 v[140:141], v[170:171], 0, v[204:205]
	global_load_dwordx4 v[140:143], v[140:141], off
	v_or_b32_e32 v186, 48, v192
	v_ashrrev_i32_e32 v187, 31, v186
	v_lshlrev_b64 v[206:207], 6, v[186:187]
	v_lshl_add_u64 v[144:145], v[170:171], 0, v[206:207]
	global_load_dwordx4 v[144:147], v[144:145], off
	v_add_u32_e32 v184, 0x80, v192
	v_ashrrev_i32_e32 v185, 31, v184
	v_lshlrev_b64 v[208:209], 6, v[184:185]
	v_lshl_add_u64 v[148:149], v[170:171], 0, v[208:209]
	global_load_dwordx4 v[148:151], v[148:149], off
	v_add_u32_e32 v182, 0x90, v192
	v_ashrrev_i32_e32 v183, 31, v182
	v_lshlrev_b64 v[210:211], 6, v[182:183]
	v_lshl_add_u64 v[152:153], v[170:171], 0, v[210:211]
	global_load_dwordx4 v[152:155], v[152:153], off
	v_add_u32_e32 v180, 0xa0, v192
	v_ashrrev_i32_e32 v181, 31, v180
	v_lshlrev_b64 v[212:213], 6, v[180:181]
	v_lshl_add_u64 v[156:157], v[170:171], 0, v[212:213]
	global_load_dwordx4 v[156:159], v[156:157], off
	v_add_u32_e32 v178, 0xb0, v192
	v_ashrrev_i32_e32 v179, 31, v178
	v_lshlrev_b64 v[214:215], 6, v[178:179]
	v_lshl_add_u64 v[160:161], v[170:171], 0, v[214:215]
	global_load_dwordx4 v[160:163], v[160:161], off
	v_xor_b32_e32 v232, 64, v224
	v_xor_b32_e32 v225, 0x80, v224
	v_lshl_or_b32 v198, s12, 8, v222
	v_ashrrev_i32_e32 v199, 31, v198
	v_lshlrev_b64 v[218:219], 11, v[192:193]
	v_lshl_add_u32 v224, v192, 10, v198
	v_lshlrev_b32_e32 v224, 1, v224
	global_load_dwordx4 v[164:167], v224, s[44:45]
	global_load_dwordx4 v[168:171], v224, s[44:45] offset:256
	v_lshl_add_u32 v224, v190, 10, v198
	v_lshlrev_b32_e32 v224, 1, v224
	global_load_dwordx4 v[174:177], v224, s[44:45]
	global_load_dwordx4 v[220:223], v224, s[44:45] offset:256
	s_and_b64 vcc, exec, s[28:29]
	s_waitcnt vmcnt(4)
	v_mov_b32_e32 v216, v133
	v_mov_b32_e32 v217, v134
	v_mov_b32_e32 v133, v135
	v_pk_add_f32 v[132:133], v[216:217], v[132:133]
	s_nop 0
	v_add_f32_e32 v132, v132, v133
	ds_bpermute_b32 v133, v232, v132
	s_waitcnt lgkmcnt(0)
	v_add_f32_e32 v132, v132, v133
	ds_bpermute_b32 v133, v225, v132
	s_waitcnt lgkmcnt(0)
	v_add_f32_e32 v132, v132, v133
	v_fmamk_f32 v132, v132, 0x3a800000, v226
	v_rsq_f32_e32 v216, v132
	v_add_f32_e32 v132, v136, v137
	v_add_f32_e32 v133, v138, v139
	v_add_f32_e32 v132, v132, v133
	ds_bpermute_b32 v133, v232, v132
	v_pk_mul_f32 v[128:129], v[128:129], v[216:217] op_sel_hi:[1,0]
	v_pk_mul_f32 v[130:131], v[130:131], v[216:217] op_sel_hi:[1,0]
	v_pk_mul_f32 v[128:129], v[128:129], s[14:15] op_sel_hi:[1,0]
	v_pk_mul_f32 v[130:131], v[130:131], s[14:15] op_sel_hi:[1,0]
	s_waitcnt lgkmcnt(0)
	v_add_f32_e32 v245, v132, v133
	v_add_f32_e32 v132, v140, v141
	v_add_f32_e32 v133, v142, v143
	v_add_f32_e32 v132, v132, v133
	ds_bpermute_b32 v133, v232, v132
	v_pk_mul_f32 v[124:125], v[124:125], v[216:217] op_sel_hi:[1,0]
	v_pk_mul_f32 v[126:127], v[126:127], v[216:217] op_sel_hi:[1,0]
	v_exp_f32_e32 v128, v128
	v_exp_f32_e32 v129, v129
	s_waitcnt lgkmcnt(0)
	v_add_f32_e32 v243, v132, v133
	v_add_f32_e32 v132, v144, v145
	v_add_f32_e32 v133, v146, v147
	v_add_f32_e32 v132, v132, v133
	ds_bpermute_b32 v133, v232, v132
	v_exp_f32_e32 v130, v130
	v_exp_f32_e32 v131, v131
	v_pk_mul_f32 v[126:127], v[126:127], s[14:15] op_sel_hi:[1,0]
	v_pk_mul_f32 v[124:125], v[124:125], s[14:15] op_sel_hi:[1,0]
	s_waitcnt lgkmcnt(0)
	v_add_f32_e32 v241, v132, v133
	v_add_f32_e32 v132, v148, v149
	v_add_f32_e32 v133, v150, v151
	v_add_f32_e32 v132, v132, v133
	ds_bpermute_b32 v133, v232, v132
	v_exp_f32_e32 v124, v124
	v_exp_f32_e32 v125, v125
	v_exp_f32_e32 v126, v126
	v_exp_f32_e32 v127, v127
	s_waitcnt lgkmcnt(0)
	v_add_f32_e32 v239, v132, v133
	v_add_f32_e32 v132, v152, v153
	v_add_f32_e32 v133, v154, v155
	v_add_f32_e32 v132, v132, v133
	ds_bpermute_b32 v133, v232, v132
	v_pk_add_f32 v[130:131], v[130:131], 1.0 op_sel_hi:[1,0]
	v_pk_add_f32 v[128:129], v[128:129], 1.0 op_sel_hi:[1,0]
	v_rcp_f32_e32 v130, v130
	v_rcp_f32_e32 v128, v128
	s_waitcnt lgkmcnt(0)
	v_add_f32_e32 v237, v132, v133
	v_add_f32_e32 v132, v156, v157
	v_add_f32_e32 v133, v158, v159
	v_add_f32_e32 v132, v132, v133
	ds_bpermute_b32 v133, v232, v132
	v_rcp_f32_e32 v129, v129
	v_rcp_f32_e32 v131, v131
	v_pk_add_f32 v[126:127], v[126:127], 1.0 op_sel_hi:[1,0]
	v_pk_add_f32 v[124:125], v[124:125], 1.0 op_sel_hi:[1,0]
	s_waitcnt lgkmcnt(0)
	v_add_f32_e32 v235, v132, v133
	v_add_f32_e32 v132, v160, v161
	v_add_f32_e32 v133, v162, v163
	v_add_f32_e32 v132, v132, v133
	ds_bpermute_b32 v133, v232, v132
	ds_bpermute_b32 v246, v225, v245
	ds_bpermute_b32 v244, v225, v243
	ds_bpermute_b32 v242, v225, v241
	ds_bpermute_b32 v240, v225, v239
	s_waitcnt lgkmcnt(4)
	v_add_f32_e32 v233, v132, v133
	v_lshlrev_b64 v[132:133], 10, v[192:193]
	v_lshl_add_u64 v[132:133], v[132:133], 0, v[198:199]
	v_lshlrev_b64 v[132:133], 1, v[132:133]
	v_lshl_add_u64 v[134:135], s[42:43], 0, v[132:133]
	global_load_dwordx4 v[156:159], v[134:135], off
	v_or_b32_e32 v132, 0x100, v132
	v_lshl_add_u64 v[134:135], s[42:43], 0, v[132:133]
	global_load_dwordx4 v[148:151], v[134:135], off
	v_lshlrev_b64 v[132:133], 10, v[190:191]
	v_lshl_add_u64 v[132:133], v[132:133], 0, v[198:199]
	v_lshlrev_b64 v[136:137], 1, v[132:133]
	v_lshl_add_u64 v[132:133], s[42:43], 0, v[136:137]
	global_load_dwordx4 v[140:143], v[132:133], off
	v_or_b32_e32 v136, 0x100, v136
	v_lshl_add_u64 v[132:133], s[42:43], 0, v[136:137]
	global_load_dwordx4 v[132:135], v[132:133], off
	ds_bpermute_b32 v238, v225, v237
	ds_bpermute_b32 v236, v225, v235
	s_waitcnt vmcnt(4)
	v_mov_b32_e32 v160, v164
	v_mov_b32_e32 v161, v165
	v_mov_b32_e32 v162, v166
	v_mov_b32_e32 v163, v167
	v_mov_b32_e32 v152, v168
	v_mov_b32_e32 v153, v169
	v_mov_b32_e32 v154, v170
	v_mov_b32_e32 v155, v171
	v_mov_b32_e32 v144, v174
	v_mov_b32_e32 v145, v175
	v_mov_b32_e32 v146, v176
	v_mov_b32_e32 v147, v177
	v_mov_b32_e32 v136, v220
	v_mov_b32_e32 v137, v221
	v_mov_b32_e32 v138, v222
	v_mov_b32_e32 v139, v223
	v_lshl_add_u32 v224, v188, 10, v198
	v_lshlrev_b32_e32 v224, 1, v224
	global_load_dwordx4 v[164:167], v224, s[44:45]
	global_load_dwordx4 v[168:171], v224, s[44:45] offset:256
	v_lshl_add_u32 v224, v186, 10, v198
	v_lshlrev_b32_e32 v224, 1, v224
	global_load_dwordx4 v[174:177], v224, s[44:45]
	global_load_dwordx4 v[220:223], v224, s[44:45] offset:256
	ds_bpermute_b32 v234, v225, v233
	v_rcp_f32_e32 v194, v124
	v_rcp_f32_e32 v195, v125
	v_rcp_f32_e32 v196, v126
	v_rcp_f32_e32 v197, v127
	s_waitcnt vmcnt(7)
	v_lshlrev_b32_e32 v126, 16, v156
	v_and_b32_e32 v127, 0xffff0000, v156
	v_lshlrev_b32_e32 v124, 16, v157
	s_waitcnt vmcnt(7)
	v_lshlrev_b32_e32 v248, 16, v160
	v_and_b32_e32 v249, 0xffff0000, v160
	v_lshlrev_b32_e32 v160, 16, v161
	v_and_b32_e32 v161, 0xffff0000, v161
	v_and_b32_e32 v125, 0xffff0000, v157
	v_lshlrev_b32_e32 v230, 16, v162
	v_and_b32_e32 v231, 0xffff0000, v162
	v_lshlrev_b32_e32 v162, 16, v163
	v_and_b32_e32 v163, 0xffff0000, v163
	v_pk_fma_f32 v[124:125], v[130:131], v[160:161], v[124:125]
	v_pk_fma_f32 v[126:127], v[128:129], v[248:249], v[126:127]
	v_lshlrev_b32_e32 v128, 16, v158
	v_and_b32_e32 v129, 0xffff0000, v158
	v_lshlrev_b32_e32 v130, 16, v159
	v_and_b32_e32 v131, 0xffff0000, v159
	v_lshl_add_u64 v[156:157], s[72:73], 0, v[218:219]
	v_pk_fma_f32 v[128:129], v[194:195], v[230:231], v[128:129]
	v_pk_fma_f32 v[130:131], v[196:197], v[162:163], v[130:131]
	v_lshl_add_u64 v[156:157], v[198:199], 1, v[156:157]
	s_cbranch_vccz .LBB0_436
	v_cvt_pk_bf16_f32 v158, v126, v127
	v_cvt_pk_bf16_f32 v159, v124, v125
	v_cvt_pk_bf16_f32 v160, v128, v129
	v_cvt_pk_bf16_f32 v161, v130, v131
	global_store_dwordx4 v[156:157], v[158:161], off

.LBB0_446:
	s_or_b64 exec, exec, s[4:5]
	v_add_f32_e32 v100, v243, v244
	v_fmamk_f32 v100, v100, 0x3a800000, v226
	v_rsq_f32_e32 v156, v100
	s_waitcnt lgkmcnt(0)
	v_lshlrev_b64 v[100:101], 10, v[188:189]
	v_lshl_add_u64 v[100:101], v[100:101], 0, v[198:199]
	v_lshlrev_b64 v[100:101], 1, v[100:101]
	v_lshl_add_u64 v[102:103], s[42:43], 0, v[100:101]
	global_load_dwordx4 v[160:163], v[102:103], off
	v_or_b32_e32 v100, 0x100, v100
	v_lshl_add_u64 v[102:103], s[42:43], 0, v[100:101]
	global_load_dwordx4 v[116:119], v[102:103], off
	v_lshlrev_b64 v[100:101], 10, v[186:187]
	v_lshl_add_u64 v[100:101], v[100:101], 0, v[198:199]
	v_lshlrev_b64 v[104:105], 1, v[100:101]
	v_lshl_add_u64 v[100:101], s[42:43], 0, v[104:105]
	global_load_dwordx4 v[108:111], v[100:101], off
	v_or_b32_e32 v104, 0x100, v104
	v_lshl_add_u64 v[100:101], s[42:43], 0, v[104:105]
	global_load_dwordx4 v[100:103], v[100:101], off
	v_pk_mul_f32 v[96:97], v[96:97], v[156:157] op_sel_hi:[1,0]
	v_pk_mul_f32 v[98:99], v[98:99], v[156:157] op_sel_hi:[1,0]
	s_waitcnt vmcnt(4)
	v_mov_b32_e32 v216, v164
	v_mov_b32_e32 v217, v165
	v_mov_b32_e32 v218, v166
	v_mov_b32_e32 v219, v167
	v_mov_b32_e32 v120, v168
	v_mov_b32_e32 v121, v169
	v_mov_b32_e32 v122, v170
	v_mov_b32_e32 v123, v171
	v_mov_b32_e32 v112, v174
	v_mov_b32_e32 v113, v175
	v_mov_b32_e32 v114, v176
	v_mov_b32_e32 v115, v177
	v_mov_b32_e32 v104, v220
	v_mov_b32_e32 v105, v221
	v_mov_b32_e32 v106, v222
	v_mov_b32_e32 v107, v223
	v_lshl_add_u32 v224, v184, 10, v198
	v_lshlrev_b32_e32 v224, 1, v224
	global_load_dwordx4 v[164:167], v224, s[44:45]
	global_load_dwordx4 v[168:171], v224, s[44:45] offset:256
	v_lshl_add_u32 v224, v182, 10, v198
	v_lshlrev_b32_e32 v224, 1, v224
	global_load_dwordx4 v[174:177], v224, s[44:45]
	global_load_dwordx4 v[220:223], v224, s[44:45] offset:256
	v_pk_mul_f32 v[96:97], v[96:97], s[14:15] op_sel_hi:[1,0]
	v_pk_mul_f32 v[98:99], v[98:99], s[14:15] op_sel_hi:[1,0]
	v_pk_mul_f32 v[92:93], v[92:93], v[156:157] op_sel_hi:[1,0]
	v_pk_mul_f32 v[94:95], v[94:95], v[156:157] op_sel_hi:[1,0]
	v_exp_f32_e32 v96, v96
	v_exp_f32_e32 v97, v97
	v_exp_f32_e32 v98, v98
	v_exp_f32_e32 v99, v99
	v_pk_mul_f32 v[94:95], v[94:95], s[14:15] op_sel_hi:[1,0]
	v_pk_mul_f32 v[92:93], v[92:93], s[14:15] op_sel_hi:[1,0]
	v_exp_f32_e32 v94, v94
	v_exp_f32_e32 v92, v92
	v_exp_f32_e32 v93, v93
	v_exp_f32_e32 v95, v95
	v_pk_add_f32 v[98:99], v[98:99], 1.0 op_sel_hi:[1,0]
	v_pk_add_f32 v[96:97], v[96:97], 1.0 op_sel_hi:[1,0]
	v_pk_add_f32 v[92:93], v[92:93], 1.0 op_sel_hi:[1,0]
	v_rcp_f32_e32 v194, v96
	v_rcp_f32_e32 v195, v97
	v_rcp_f32_e32 v96, v98
	v_rcp_f32_e32 v97, v99
	v_pk_add_f32 v[94:95], v[94:95], 1.0 op_sel_hi:[1,0]
	v_rcp_f32_e32 v92, v92
	v_rcp_f32_e32 v93, v93
	v_lshlrev_b64 v[158:159], 11, v[188:189]
	v_lshl_add_u64 v[158:159], s[72:73], 0, v[158:159]
	s_and_b64 vcc, exec, s[28:29]
	v_lshl_add_u64 v[158:159], v[198:199], 1, v[158:159]
	s_waitcnt vmcnt(7)
	v_lshlrev_b32_e32 v230, 16, v160
	v_and_b32_e32 v231, 0xffff0000, v160
	v_lshlrev_b32_e32 v160, 16, v161
	s_waitcnt vmcnt(7)
	v_lshlrev_b32_e32 v98, 16, v216
	v_and_b32_e32 v99, 0xffff0000, v216
	v_lshlrev_b32_e32 v196, 16, v217
	v_and_b32_e32 v197, 0xffff0000, v217
	v_rcp_f32_e32 v216, v94
	v_rcp_f32_e32 v217, v95
	v_and_b32_e32 v161, 0xffff0000, v161
	v_lshlrev_b32_e32 v94, 16, v218
	v_and_b32_e32 v95, 0xffff0000, v218
	v_lshlrev_b32_e32 v218, 16, v219
	v_and_b32_e32 v219, 0xffff0000, v219
	v_pk_fma_f32 v[96:97], v[96:97], v[196:197], v[160:161]
	v_lshlrev_b32_e32 v160, 16, v162
	v_and_b32_e32 v161, 0xffff0000, v162
	v_lshlrev_b32_e32 v162, 16, v163
	v_and_b32_e32 v163, 0xffff0000, v163
	v_pk_fma_f32 v[98:99], v[194:195], v[98:99], v[230:231]
	v_pk_fma_f32 v[94:95], v[92:93], v[94:95], v[160:161]
	v_pk_fma_f32 v[92:93], v[216:217], v[218:219], v[162:163]
	s_cbranch_vccz .LBB0_448
	v_cvt_pk_bf16_f32 v160, v98, v99
	v_cvt_pk_bf16_f32 v161, v96, v97
	v_cvt_pk_bf16_f32 v162, v94, v95
	v_cvt_pk_bf16_f32 v163, v92, v93
	global_store_dwordx4 v[158:159], v[160:163], off

.LBB0_458:
	s_or_b64 exec, exec, s[4:5]
	v_add_f32_e32 v68, v239, v240
	v_fmamk_f32 v68, v68, 0x3a800000, v226
	v_rsq_f32_e32 v156, v68
	s_waitcnt lgkmcnt(0)
	v_lshlrev_b64 v[68:69], 10, v[184:185]
	v_lshl_add_u64 v[68:69], v[68:69], 0, v[198:199]
	v_lshlrev_b64 v[68:69], 1, v[68:69]
	v_lshl_add_u64 v[70:71], s[42:43], 0, v[68:69]
	global_load_dwordx4 v[160:163], v[70:71], off
	v_or_b32_e32 v68, 0x100, v68
	v_lshl_add_u64 v[70:71], s[42:43], 0, v[68:69]
	global_load_dwordx4 v[84:87], v[70:71], off
	v_lshlrev_b64 v[68:69], 10, v[182:183]
	v_lshl_add_u64 v[68:69], v[68:69], 0, v[198:199]
	v_lshlrev_b64 v[72:73], 1, v[68:69]
	v_lshl_add_u64 v[68:69], s[42:43], 0, v[72:73]
	global_load_dwordx4 v[76:79], v[68:69], off
	v_or_b32_e32 v72, 0x100, v72
	v_lshl_add_u64 v[68:69], s[42:43], 0, v[72:73]
	global_load_dwordx4 v[68:71], v[68:69], off
	v_pk_mul_f32 v[64:65], v[64:65], v[156:157] op_sel_hi:[1,0]
	v_pk_mul_f32 v[66:67], v[66:67], v[156:157] op_sel_hi:[1,0]
	s_waitcnt vmcnt(4)
	v_mov_b32_e32 v216, v164
	v_mov_b32_e32 v217, v165
	v_mov_b32_e32 v218, v166
	v_mov_b32_e32 v219, v167
	v_mov_b32_e32 v88, v168
	v_mov_b32_e32 v89, v169
	v_mov_b32_e32 v90, v170
	v_mov_b32_e32 v91, v171
	v_mov_b32_e32 v80, v174
	v_mov_b32_e32 v81, v175
	v_mov_b32_e32 v82, v176
	v_mov_b32_e32 v83, v177
	v_mov_b32_e32 v72, v220
	v_mov_b32_e32 v73, v221
	v_mov_b32_e32 v74, v222
	v_mov_b32_e32 v75, v223
	v_lshl_add_u32 v224, v180, 10, v198
	v_lshlrev_b32_e32 v224, 1, v224
	global_load_dwordx4 v[164:167], v224, s[44:45]
	global_load_dwordx4 v[168:171], v224, s[44:45] offset:256
	v_lshl_add_u32 v224, v178, 10, v198
	v_lshlrev_b32_e32 v224, 1, v224
	global_load_dwordx4 v[174:177], v224, s[44:45]
	global_load_dwordx4 v[220:223], v224, s[44:45] offset:256
	v_pk_mul_f32 v[64:65], v[64:65], s[14:15] op_sel_hi:[1,0]
	v_pk_mul_f32 v[66:67], v[66:67], s[14:15] op_sel_hi:[1,0]
	v_pk_mul_f32 v[60:61], v[60:61], v[156:157] op_sel_hi:[1,0]
	v_pk_mul_f32 v[62:63], v[62:63], v[156:157] op_sel_hi:[1,0]
	v_exp_f32_e32 v64, v64
	v_exp_f32_e32 v65, v65
	v_exp_f32_e32 v66, v66
	v_exp_f32_e32 v67, v67
	v_pk_mul_f32 v[62:63], v[62:63], s[14:15] op_sel_hi:[1,0]
	v_pk_mul_f32 v[60:61], v[60:61], s[14:15] op_sel_hi:[1,0]
	v_exp_f32_e32 v62, v62
	v_exp_f32_e32 v60, v60
	v_exp_f32_e32 v61, v61
	v_exp_f32_e32 v63, v63
	v_pk_add_f32 v[66:67], v[66:67], 1.0 op_sel_hi:[1,0]
	v_pk_add_f32 v[64:65], v[64:65], 1.0 op_sel_hi:[1,0]
	v_pk_add_f32 v[60:61], v[60:61], 1.0 op_sel_hi:[1,0]
	v_rcp_f32_e32 v194, v64
	v_rcp_f32_e32 v195, v65
	v_rcp_f32_e32 v64, v66
	v_rcp_f32_e32 v65, v67
	v_pk_add_f32 v[62:63], v[62:63], 1.0 op_sel_hi:[1,0]
	v_rcp_f32_e32 v60, v60
	v_rcp_f32_e32 v61, v61
	v_lshlrev_b64 v[158:159], 11, v[184:185]
	v_lshl_add_u64 v[158:159], s[72:73], 0, v[158:159]
	s_and_b64 vcc, exec, s[28:29]
	v_lshl_add_u64 v[158:159], v[198:199], 1, v[158:159]
	s_waitcnt vmcnt(7)
	v_lshlrev_b32_e32 v230, 16, v160
	v_and_b32_e32 v231, 0xffff0000, v160
	v_lshlrev_b32_e32 v160, 16, v161
	s_waitcnt vmcnt(7)
	v_lshlrev_b32_e32 v66, 16, v216
	v_and_b32_e32 v67, 0xffff0000, v216
	v_lshlrev_b32_e32 v196, 16, v217
	v_and_b32_e32 v197, 0xffff0000, v217
	v_rcp_f32_e32 v216, v62
	v_rcp_f32_e32 v217, v63
	v_and_b32_e32 v161, 0xffff0000, v161
	v_lshlrev_b32_e32 v62, 16, v218
	v_and_b32_e32 v63, 0xffff0000, v218
	v_lshlrev_b32_e32 v218, 16, v219
	v_and_b32_e32 v219, 0xffff0000, v219
	v_pk_fma_f32 v[64:65], v[64:65], v[196:197], v[160:161]
	v_lshlrev_b32_e32 v160, 16, v162
	v_and_b32_e32 v161, 0xffff0000, v162
	v_lshlrev_b32_e32 v162, 16, v163
	v_and_b32_e32 v163, 0xffff0000, v163
	v_pk_fma_f32 v[66:67], v[194:195], v[66:67], v[230:231]
	v_pk_fma_f32 v[62:63], v[60:61], v[62:63], v[160:161]
	v_pk_fma_f32 v[60:61], v[216:217], v[218:219], v[162:163]
	s_cbranch_vccz .LBB0_460
	v_cvt_pk_bf16_f32 v160, v66, v67
	v_cvt_pk_bf16_f32 v161, v64, v65
	v_cvt_pk_bf16_f32 v162, v62, v63
	v_cvt_pk_bf16_f32 v163, v60, v61
	global_store_dwordx4 v[158:159], v[160:163], off

; #define LAS __attribute__((address_space(3)))
; __device__ __forceinline__ void cv_background(Frame& F, const CvPtrs& P, int s) {
;     int tv = threadIdx.x; asm volatile("" : "+v"(tv));
;     const int w = __builtin_amdgcn_readfirstlane(tv >> 6) - 1, lane = tv & 63, nbw = F.G * (NWAVES - 1);
;     LAS float* scr = (LAS float*)(F.lds + RING_OFF + (w + 1) * 16384);
;     const int sh_ = cv_bg_share(s), hi = (sh_ + 1) * CV_BG_PER < CV_BG_TOTAL ? (sh_ + 1) * CV_BG_PER : CV_BG_TOTAL;
;     for (int j = sh_ * CV_BG_PER + F.vcu * (NWAVES - 1) + w; j < hi; j += nbw) {
; __device__ __forceinline__ void xcd_barrier_cv(const XcdBarrier& b, Frame& F, const CvPtrs& P, int s, bool local) {
;     ...
;     else if (cv_bg_share(s) >= 0 && cv_bg_share(s) < CV_BG_SHARES) cv_background(F, P, s);
.LBB0_769:
	s_and_b64 vcc, exec, s[0:1]
	s_cbranch_vccz .LBB0_1015
	s_sleep 75
	s_sleep 75
	v_mov_b32_e32 v4, v0
	s_mov_b64 s[6:7], -1
	v_readfirstlane_b32 s8, v4
	s_mov_b64 s[0:1], 0
	s_cmp_lt_i32 s89, 5
	s_mov_b64 s[4:5], 0
	s_cbranch_scc1 .LBB0_787
	s_cmp_gt_i32 s89, 7
	s_cbranch_scc0 .LBB0_779
	s_cmp_gt_i32 s89, 8
	s_cbranch_scc0 .LBB0_776
	s_cmp_eq_u32 s89, 9
	s_mov_b64 s[4:5], -1
	s_cbranch_scc0 .LBB0_775
	s_mov_b64 s[4:5], 0
